# LayerNorm phases rewritten by hand: parameters loaded once per wave, stores no longer waited per chunk
# speedup vs baseline: 1.0173x; 1.0061x over previous
; DI int ltid() { int t = threadIdx.x; asm volatile("" : "+v"(t)); return t; }
; DI int lbid() { int t = blockIdx.x; asm volatile("" : "+s"(t)); return t; }
; DI float bflo(unsigned u) { return __uint_as_float(u << 16); }
; DI float bfhi(unsigned u) { return __uint_as_float(u & 0xffff0000u); }
; template <int NR>
; DI void ln_rows(const Params& P, const LnSpec& sp, int row, int stride, int lane) {
;     char* ws = P.ws; float* X = (float*)(ws + OFF_X); bf16_t* XM = (bf16_t*)(ws + OFF_XM); const float* MOD = (const float*)(ws + OFF_MOD);
;     const float* g = P.in[6] + (sp.l * 3 + sp.which) * 1024; const float* bb = P.in[7] + (sp.l * 3 + sp.which) * 1024;
;     f32x4 v[NR][4]; float s[NR], qv[NR];
; #pragma unroll
;     for (int k = 0; k < NR; ++k) {
;         const int r = row + k * stride;
;         const float* xp = r < RL ? sp.res_lat + (size_t)r * 1024 : sp.res_ctx + (size_t)(r - RL) * 1024;
;         const bf16_t* yp = sp.Y + (size_t)r * 1024;
; #pragma unroll
;         for (int i = 0; i < 4; ++i) {
;             const f32x4 x = __builtin_nontemporal_load((const f32x4*)(xp + (i * 64 + lane) * 4));
;             const u32x2 y = __builtin_nontemporal_load((const u32x2*)(yp + (i * 64 + lane) * 4));
;             v[k][i][0] = ALPHA * x[0] + bflo(y.x); v[k][i][1] = ALPHA * x[1] + bfhi(y.x);
;             v[k][i][2] = ALPHA * x[2] + bflo(y.y); v[k][i][3] = ALPHA * x[3] + bfhi(y.y);
;         }
;     }
; DI void phase_ln(const Params& P, int l, int which, int lnext, int mshift, bool final_, bool lat_only, const bf16_t* Y, bool first) {
;     float* X = (float*)(P.ws + OFF_X);
;     const LnSpec sp{l, which, lnext, mshift, final_, nullptr, Y, first ? P.in[0] : X, first ? P.in[2] : X + (size_t)RL * 1024};
;     const int lane = ltid() & 63, wave = ltid() >> 6;
;     const int nq = ((final_ || lat_only) ? RL : RT) / 4;
;     for (int q = lbid() * NWAVE + wave; q < nq; q += gridDim.x * NWAVE) ln_rows<4>(P, sp, 4 * q, 1, lane);
.Lmy_ln1_entry:
	v_readlane_b32 s0, v253, 0
	v_readlane_b32 s2, v253, 9
	v_readlane_b32 s3, v253, 10
	v_readlane_b32 s8, v254, 59
	v_lshrrev_b32_e32 v224, 6, v194
	s_nop 3
	s_load_dword s9, s[2:3], 0x0
	v_readfirstlane_b32 s1, v224
	v_lshlrev_b32_e32 v170, 4, v197
	v_lshlrev_b32_e32 v171, 3, v197
	v_xor_b32_e32 v160, 32, v197
	v_xor_b32_e32 v161, 16, v197
	v_xor_b32_e32 v162, 8, v197
	v_xor_b32_e32 v163, 4, v197
	v_xor_b32_e32 v164, 2, v197
	v_xor_b32_e32 v165, 1, v197
	v_lshlrev_b32_e32 v160, 2, v160
	v_lshlrev_b32_e32 v161, 2, v161
	v_lshlrev_b32_e32 v162, 2, v162
	v_lshlrev_b32_e32 v163, 2, v163
	v_lshlrev_b32_e32 v164, 2, v164
	v_lshlrev_b32_e32 v165, 2, v165
	v_mov_b32_e32 v228, 0x3a800000
	s_waitcnt lgkmcnt(0)
	s_sub_u32 s2, s2, 0xd8
	s_subb_u32 s3, s3, 0
	s_load_dwordx2 s[10:11], s[2:3], 0x0
	s_load_dwordx2 s[12:13], s[2:3], 0x10
	s_load_dwordx2 s[14:15], s[2:3], 0x30
	s_load_dwordx2 s[98:99], s[2:3], 0x38
	s_lshl_b32 s0, s0, 3
	s_add_u32 s0, s0, s1
	s_lshl_b32 s9, s9, 3
	s_cmp_ge_u32 s8, 14
	s_cselect_b32 s18, 1, 0
	s_cmp_eq_u32 s8, 4
	s_cselect_b32 s16, 0, 2
	s_cmp_eq_u32 s8, 16
	s_cselect_b32 s16, 0, s16
	s_cmp_eq_u32 s8, 10
	s_cselect_b32 s16, 1, s16
	s_cmp_eq_u32 s8, 21
	s_cselect_b32 s16, 1, s16
	s_mul_i32 s2, s18, 3
	s_add_u32 s2, s2, s16
	s_lshl_b32 s2, s2, 12
	v_add_u32_e32 v229, s2, v170
	s_cmp_ge_u32 s8, 13
	s_cselect_b32 s2, 0x2d000, 0
	s_cmp_eq_u32 s16, 0
	s_cselect_b32 s3, 0x3000, 0
	s_cmp_eq_u32 s16, 1
	s_cselect_b32 s3, 0x6000, s3
	s_add_u32 s2, s2, s3
	s_add_u32 s2, s2, 0x4f20000
	v_add_u32_e32 v230, s2, v170
	s_waitcnt lgkmcnt(0)
	global_load_dwordx4 v[96:99], v229, s[14:15]
	global_load_dwordx4 v[100:103], v229, s[14:15] offset:1024
	global_load_dwordx4 v[104:107], v229, s[14:15] offset:2048
	global_load_dwordx4 v[108:111], v229, s[14:15] offset:3072
	global_load_dwordx4 v[112:115], v229, s[98:99]
	global_load_dwordx4 v[116:119], v229, s[98:99] offset:1024
	global_load_dwordx4 v[120:123], v229, s[98:99] offset:2048
	global_load_dwordx4 v[124:127], v229, s[98:99] offset:3072
	s_cmp_eq_u32 s16, 1
	s_mov_b32 s16, 0xd383200
	s_cselect_b32 s16, 0x11583200, s16
	s_cmp_eq_u32 s8, 24
	s_cselect_b32 s18, 1, 0
	s_cmp_eq_u32 s8, 4
	s_cbranch_scc1 .Lmy_ln1_first
	s_mov_b32 s10, s94
	s_mov_b32 s11, s95
	s_mov_b32 s12, s94
	s_mov_b32 s13, s95
	s_mov_b32 s15, 0x4f83200
	s_branch .Lmy_ln1_bases
.Lmy_ln1_first:
	s_sub_u32 s12, s12, 0x8000000
	s_subb_u32 s13, s13, 0
	s_mov_b32 s15, 0
.Lmy_ln1_bases:
	s_cmp_ge_u32 s8, 21
	s_movk_i32 s14, 0x2100
	s_cselect_b32 s14, 0x2000, s14
	s_mov_b32 s8, s0
	s_cmp_ge_u32 s8, s14
	s_cbranch_scc1 .Lmy_ln1_done
.Lmy_ln1_loop:
	s_lshl_b32 s2, s8, 14
	s_cmp_ge_u32 s8, 0x2000
	s_cselect_b32 s0, s12, s10
	s_cselect_b32 s1, s13, s11
	s_add_u32 s3, s2, s15
	v_add_u32_e32 v188, s3, v170
	s_add_u32 s3, s3, 0x1000
	v_add_u32_e32 v189, s3, v170
	s_add_u32 s3, s3, 0x1000
	v_add_u32_e32 v190, s3, v170
	s_add_u32 s3, s3, 0x1000
	v_add_u32_e32 v191, s3, v170
	s_lshr_b32 s3, s2, 1
	s_add_u32 s3, s3, s16
	v_add_u32_e32 v192, s3, v171
	s_add_u32 s3, s3, 0x1000
	v_add_u32_e32 v193, s3, v171
	global_load_dwordx4 v[0:3], v188, s[0:1] nt
	global_load_dwordx4 v[4:7], v188, s[0:1] offset:1024 nt
	global_load_dwordx4 v[8:11], v188, s[0:1] offset:2048 nt
	global_load_dwordx4 v[12:15], v188, s[0:1] offset:3072 nt
	global_load_dwordx2 v[64:65], v192, s[94:95] nt
	global_load_dwordx2 v[66:67], v192, s[94:95] offset:512 nt
	global_load_dwordx2 v[68:69], v192, s[94:95] offset:1024 nt
	global_load_dwordx2 v[70:71], v192, s[94:95] offset:1536 nt
	global_load_dwordx4 v[16:19], v189, s[0:1] nt
	global_load_dwordx4 v[20:23], v189, s[0:1] offset:1024 nt
	global_load_dwordx4 v[24:27], v189, s[0:1] offset:2048 nt
	global_load_dwordx4 v[28:31], v189, s[0:1] offset:3072 nt
	global_load_dwordx2 v[72:73], v192, s[94:95] offset:2048 nt
	global_load_dwordx2 v[74:75], v192, s[94:95] offset:2560 nt
	global_load_dwordx2 v[76:77], v192, s[94:95] offset:3072 nt
	global_load_dwordx2 v[78:79], v192, s[94:95] offset:3584 nt
	global_load_dwordx4 v[32:35], v190, s[0:1] nt
	global_load_dwordx4 v[36:39], v190, s[0:1] offset:1024 nt
	global_load_dwordx4 v[40:43], v190, s[0:1] offset:2048 nt
	global_load_dwordx4 v[44:47], v190, s[0:1] offset:3072 nt
	global_load_dwordx2 v[80:81], v193, s[94:95] nt
	global_load_dwordx2 v[82:83], v193, s[94:95] offset:512 nt
	global_load_dwordx2 v[84:85], v193, s[94:95] offset:1024 nt
	global_load_dwordx2 v[86:87], v193, s[94:95] offset:1536 nt
	global_load_dwordx4 v[48:51], v191, s[0:1] nt
	global_load_dwordx4 v[52:55], v191, s[0:1] offset:1024 nt
	global_load_dwordx4 v[56:59], v191, s[0:1] offset:2048 nt
	global_load_dwordx4 v[60:63], v191, s[0:1] offset:3072 nt
	global_load_dwordx2 v[88:89], v193, s[94:95] offset:2048 nt
	global_load_dwordx2 v[90:91], v193, s[94:95] offset:2560 nt
	global_load_dwordx2 v[92:93], v193, s[94:95] offset:3072 nt
	global_load_dwordx2 v[94:95], v193, s[94:95] offset:3584 nt
	s_cmp_eq_u32 s18, 1
	s_cbranch_scc1 .Lmy_ln1_nomod
	s_lshr_b32 s3, s8, 11
	s_mul_i32 s3, s3, 0x9000
	v_add_u32_e32 v224, s3, v230
	v_add_u32_e32 v225, 0x1000, v224
	global_load_dwordx4 v[128:131], v224, s[94:95]
	global_load_dwordx4 v[132:135], v224, s[94:95] offset:1024
	global_load_dwordx4 v[136:139], v224, s[94:95] offset:2048
	global_load_dwordx4 v[140:143], v224, s[94:95] offset:3072
	global_load_dwordx4 v[144:147], v225, s[94:95]
	global_load_dwordx4 v[148:151], v225, s[94:95] offset:1024
	global_load_dwordx4 v[152:155], v225, s[94:95] offset:2048
	global_load_dwordx4 v[156:159], v225, s[94:95] offset:3072
	s_waitcnt vmcnt(32)
	s_branch .Lmy_ln1_row0
.Lmy_ln1_nomod:
	s_waitcnt vmcnt(24)
; DI float bflo(unsigned u) { return __uint_as_float(u << 16); }
; DI float bfhi(unsigned u) { return __uint_as_float(u & 0xffff0000u); }
; template <int NR>
; DI void ln_rows(const Params& P, const LnSpec& sp, int row, int stride, int lane) {
;     ...
;     for (int k = 0; k < NR; ++k) {
;         const int r = row + k * stride;
;         const float* xp = r < RL ? sp.res_lat + (size_t)r * 1024 : sp.res_ctx + (size_t)(r - RL) * 1024;
;         const bf16_t* yp = sp.Y + (size_t)r * 1024;
; #pragma unroll
;         for (int i = 0; i < 4; ++i) {
;             const f32x4 x = __builtin_nontemporal_load((const f32x4*)(xp + (i * 64 + lane) * 4));
;             const u32x2 y = __builtin_nontemporal_load((const u32x2*)(yp + (i * 64 + lane) * 4));
;             v[k][i][0] = ALPHA * x[0] + bflo(y.x); v[k][i][1] = ALPHA * x[1] + bfhi(y.x);
;             v[k][i][2] = ALPHA * x[2] + bflo(y.y); v[k][i][3] = ALPHA * x[3] + bfhi(y.y);
;         }
;     }
; #pragma unroll
;     for (int k = 0; k < NR; ++k) {
;         s[k] = 0.f;
; #pragma unroll
;         for (int i = 0; i < 4; ++i) s[k] += (v[k][i][0] + v[k][i][1]) + (v[k][i][2] + v[k][i][3]);
.Lmy_ln1_row0:
	s_cmp_eq_u32 s18, 1
	s_cselect_b32 s3, 0, 0x4f83200
	s_add_u32 s3, s3, s2
	v_add_u32_e32 v218, s3, v170
	s_add_u32 s3, s3, 0x1000
	v_add_u32_e32 v219, s3, v170
	s_add_u32 s3, s3, 0x1000
	v_add_u32_e32 v220, s3, v170
	s_add_u32 s3, s3, 0x1000
	v_add_u32_e32 v221, s3, v170
	s_lshr_b32 s3, s2, 1
	s_add_u32 s3, s3, 0xd383200
	v_add_u32_e32 v222, s3, v171
	s_add_u32 s3, s3, 0x1000
	v_add_u32_e32 v223, s3, v171
	v_lshlrev_b32_e32 v224, 16, v64
	v_and_b32_e32 v225, 0xffff0000, v64
	v_fmamk_f32 v0, v0, 0x3fb504f3, v224
	v_fmamk_f32 v1, v1, 0x3fb504f3, v225
	v_lshlrev_b32_e32 v224, 16, v65
	v_and_b32_e32 v225, 0xffff0000, v65
	v_fmamk_f32 v2, v2, 0x3fb504f3, v224
	v_fmamk_f32 v3, v3, 0x3fb504f3, v225
	v_add_f32_e32 v226, v0, v1
	v_add_f32_e32 v227, v2, v3
	v_add_f32_e32 v226, v226, v227
	v_mov_b32_e32 v166, v226
	v_lshlrev_b32_e32 v224, 16, v66
	v_and_b32_e32 v225, 0xffff0000, v66
	v_fmamk_f32 v4, v4, 0x3fb504f3, v224
	v_fmamk_f32 v5, v5, 0x3fb504f3, v225
	v_lshlrev_b32_e32 v224, 16, v67
	v_and_b32_e32 v225, 0xffff0000, v67
	v_fmamk_f32 v6, v6, 0x3fb504f3, v224
	v_fmamk_f32 v7, v7, 0x3fb504f3, v225
	v_add_f32_e32 v226, v4, v5
	v_add_f32_e32 v227, v6, v7
	v_add_f32_e32 v226, v226, v227
	v_add_f32_e32 v166, v166, v226
	v_lshlrev_b32_e32 v224, 16, v68
	v_and_b32_e32 v225, 0xffff0000, v68
	v_fmamk_f32 v8, v8, 0x3fb504f3, v224
	v_fmamk_f32 v9, v9, 0x3fb504f3, v225
	v_lshlrev_b32_e32 v224, 16, v69
	v_and_b32_e32 v225, 0xffff0000, v69
	v_fmamk_f32 v10, v10, 0x3fb504f3, v224
	v_fmamk_f32 v11, v11, 0x3fb504f3, v225
	v_add_f32_e32 v226, v8, v9
	v_add_f32_e32 v227, v10, v11
	v_add_f32_e32 v226, v226, v227
	v_add_f32_e32 v166, v166, v226
	v_lshlrev_b32_e32 v224, 16, v70
	v_and_b32_e32 v225, 0xffff0000, v70
	v_fmamk_f32 v12, v12, 0x3fb504f3, v224
	v_fmamk_f32 v13, v13, 0x3fb504f3, v225
	v_lshlrev_b32_e32 v224, 16, v71
	v_and_b32_e32 v225, 0xffff0000, v71
	v_fmamk_f32 v14, v14, 0x3fb504f3, v224
	v_fmamk_f32 v15, v15, 0x3fb504f3, v225
	v_add_f32_e32 v226, v12, v13
	v_add_f32_e32 v227, v14, v15
	v_add_f32_e32 v226, v226, v227
	v_add_f32_e32 v166, v166, v226
	s_waitcnt vmcnt(16)
	v_lshlrev_b32_e32 v224, 16, v72
	v_and_b32_e32 v225, 0xffff0000, v72
	v_fmamk_f32 v16, v16, 0x3fb504f3, v224
	v_fmamk_f32 v17, v17, 0x3fb504f3, v225
	v_lshlrev_b32_e32 v224, 16, v73
	v_and_b32_e32 v225, 0xffff0000, v73
	v_fmamk_f32 v18, v18, 0x3fb504f3, v224
	v_fmamk_f32 v19, v19, 0x3fb504f3, v225
	v_add_f32_e32 v226, v16, v17
	v_add_f32_e32 v227, v18, v19
	v_add_f32_e32 v226, v226, v227
	v_mov_b32_e32 v167, v226
	v_lshlrev_b32_e32 v224, 16, v74
	v_and_b32_e32 v225, 0xffff0000, v74
	v_fmamk_f32 v20, v20, 0x3fb504f3, v224
	v_fmamk_f32 v21, v21, 0x3fb504f3, v225
	v_lshlrev_b32_e32 v224, 16, v75
	v_and_b32_e32 v225, 0xffff0000, v75
	v_fmamk_f32 v22, v22, 0x3fb504f3, v224
	v_fmamk_f32 v23, v23, 0x3fb504f3, v225
	v_add_f32_e32 v226, v20, v21
	v_add_f32_e32 v227, v22, v23
	v_add_f32_e32 v226, v226, v227
	v_add_f32_e32 v167, v167, v226
	v_lshlrev_b32_e32 v224, 16, v76
	v_and_b32_e32 v225, 0xffff0000, v76
	v_fmamk_f32 v24, v24, 0x3fb504f3, v224
	v_fmamk_f32 v25, v25, 0x3fb504f3, v225
	v_lshlrev_b32_e32 v224, 16, v77
	v_and_b32_e32 v225, 0xffff0000, v77
	v_fmamk_f32 v26, v26, 0x3fb504f3, v224
	v_fmamk_f32 v27, v27, 0x3fb504f3, v225
	v_add_f32_e32 v226, v24, v25
	v_add_f32_e32 v227, v26, v27
	v_add_f32_e32 v226, v226, v227
	v_add_f32_e32 v167, v167, v226
	v_lshlrev_b32_e32 v224, 16, v78
	v_and_b32_e32 v225, 0xffff0000, v78
	v_fmamk_f32 v28, v28, 0x3fb504f3, v224
	v_fmamk_f32 v29, v29, 0x3fb504f3, v225
	v_lshlrev_b32_e32 v224, 16, v79
	v_and_b32_e32 v225, 0xffff0000, v79
	v_fmamk_f32 v30, v30, 0x3fb504f3, v224
	v_fmamk_f32 v31, v31, 0x3fb504f3, v225
	v_add_f32_e32 v226, v28, v29
	v_add_f32_e32 v227, v30, v31
	v_add_f32_e32 v226, v226, v227
	v_add_f32_e32 v167, v167, v226
	s_waitcnt vmcnt(8)
	v_lshlrev_b32_e32 v224, 16, v80
	v_and_b32_e32 v225, 0xffff0000, v80
	v_fmamk_f32 v32, v32, 0x3fb504f3, v224
	v_fmamk_f32 v33, v33, 0x3fb504f3, v225
	v_lshlrev_b32_e32 v224, 16, v81
	v_and_b32_e32 v225, 0xffff0000, v81
	v_fmamk_f32 v34, v34, 0x3fb504f3, v224
	v_fmamk_f32 v35, v35, 0x3fb504f3, v225
	v_add_f32_e32 v226, v32, v33
	v_add_f32_e32 v227, v34, v35
	v_add_f32_e32 v226, v226, v227
	v_mov_b32_e32 v168, v226
	v_lshlrev_b32_e32 v224, 16, v82
	v_and_b32_e32 v225, 0xffff0000, v82
	v_fmamk_f32 v36, v36, 0x3fb504f3, v224
	v_fmamk_f32 v37, v37, 0x3fb504f3, v225
	v_lshlrev_b32_e32 v224, 16, v83
	v_and_b32_e32 v225, 0xffff0000, v83
	v_fmamk_f32 v38, v38, 0x3fb504f3, v224
	v_fmamk_f32 v39, v39, 0x3fb504f3, v225
	v_add_f32_e32 v226, v36, v37
	v_add_f32_e32 v227, v38, v39
	v_add_f32_e32 v226, v226, v227
	v_add_f32_e32 v168, v168, v226
	v_lshlrev_b32_e32 v224, 16, v84
	v_and_b32_e32 v225, 0xffff0000, v84
	v_fmamk_f32 v40, v40, 0x3fb504f3, v224
	v_fmamk_f32 v41, v41, 0x3fb504f3, v225
	v_lshlrev_b32_e32 v224, 16, v85
	v_and_b32_e32 v225, 0xffff0000, v85
	v_fmamk_f32 v42, v42, 0x3fb504f3, v224
	v_fmamk_f32 v43, v43, 0x3fb504f3, v225
	v_add_f32_e32 v226, v40, v41
	v_add_f32_e32 v227, v42, v43
	v_add_f32_e32 v226, v226, v227
	v_add_f32_e32 v168, v168, v226
	v_lshlrev_b32_e32 v224, 16, v86
	v_and_b32_e32 v225, 0xffff0000, v86
	v_fmamk_f32 v44, v44, 0x3fb504f3, v224
	v_fmamk_f32 v45, v45, 0x3fb504f3, v225
	v_lshlrev_b32_e32 v224, 16, v87
	v_and_b32_e32 v225, 0xffff0000, v87
	v_fmamk_f32 v46, v46, 0x3fb504f3, v224
	v_fmamk_f32 v47, v47, 0x3fb504f3, v225
	v_add_f32_e32 v226, v44, v45
	v_add_f32_e32 v227, v46, v47
	v_add_f32_e32 v226, v226, v227
	v_add_f32_e32 v168, v168, v226
	s_waitcnt vmcnt(0)
; template <int NR>
; DI void ln_rows(const Params& P, const LnSpec& sp, int row, int stride, int lane) {
;     ...
; #pragma unroll
;     for (int k = 0; k < NR; ++k) {
;         s[k] = 0.f;
; #pragma unroll
;         for (int i = 0; i < 4; ++i) s[k] += (v[k][i][0] + v[k][i][1]) + (v[k][i][2] + v[k][i][3]);
;     }
; #pragma unroll
;     for (int o = 32; o >= 1; o >>= 1)
; #pragma unroll
;         for (int k = 0; k < NR; ++k) s[k] += __shfl_xor(s[k], o);
; #pragma unroll
;     for (int k = 0; k < NR; ++k) {
;         s[k] *= (1.f / 1024.f); qv[k] = 0.f;
; #pragma unroll
;         for (int i = 0; i < 4; ++i)
; #pragma unroll
;             for (int j = 0; j < 4; ++j) { const float d = v[k][i][j] - s[k]; qv[k] += d * d; }
;     }
	v_lshlrev_b32_e32 v224, 16, v88
	v_and_b32_e32 v225, 0xffff0000, v88
	v_fmamk_f32 v48, v48, 0x3fb504f3, v224
	v_fmamk_f32 v49, v49, 0x3fb504f3, v225
	v_lshlrev_b32_e32 v224, 16, v89
	v_and_b32_e32 v225, 0xffff0000, v89
	v_fmamk_f32 v50, v50, 0x3fb504f3, v224
	v_fmamk_f32 v51, v51, 0x3fb504f3, v225
	v_add_f32_e32 v226, v48, v49
	v_add_f32_e32 v227, v50, v51
	v_add_f32_e32 v226, v226, v227
	v_mov_b32_e32 v169, v226
	v_lshlrev_b32_e32 v224, 16, v90
	v_and_b32_e32 v225, 0xffff0000, v90
	v_fmamk_f32 v52, v52, 0x3fb504f3, v224
	v_fmamk_f32 v53, v53, 0x3fb504f3, v225
	v_lshlrev_b32_e32 v224, 16, v91
	v_and_b32_e32 v225, 0xffff0000, v91
	v_fmamk_f32 v54, v54, 0x3fb504f3, v224
	v_fmamk_f32 v55, v55, 0x3fb504f3, v225
	v_add_f32_e32 v226, v52, v53
	v_add_f32_e32 v227, v54, v55
	v_add_f32_e32 v226, v226, v227
	v_add_f32_e32 v169, v169, v226
	v_lshlrev_b32_e32 v224, 16, v92
	v_and_b32_e32 v225, 0xffff0000, v92
	v_fmamk_f32 v56, v56, 0x3fb504f3, v224
	v_fmamk_f32 v57, v57, 0x3fb504f3, v225
	v_lshlrev_b32_e32 v224, 16, v93
	v_and_b32_e32 v225, 0xffff0000, v93
	v_fmamk_f32 v58, v58, 0x3fb504f3, v224
	v_fmamk_f32 v59, v59, 0x3fb504f3, v225
	v_add_f32_e32 v226, v56, v57
	v_add_f32_e32 v227, v58, v59
	v_add_f32_e32 v226, v226, v227
	v_add_f32_e32 v169, v169, v226
	v_lshlrev_b32_e32 v224, 16, v94
	v_and_b32_e32 v225, 0xffff0000, v94
	v_fmamk_f32 v60, v60, 0x3fb504f3, v224
	v_fmamk_f32 v61, v61, 0x3fb504f3, v225
	v_lshlrev_b32_e32 v224, 16, v95
	v_and_b32_e32 v225, 0xffff0000, v95
	v_fmamk_f32 v62, v62, 0x3fb504f3, v224
	v_fmamk_f32 v63, v63, 0x3fb504f3, v225
	v_add_f32_e32 v226, v60, v61
	v_add_f32_e32 v227, v62, v63
	v_add_f32_e32 v226, v226, v227
	v_add_f32_e32 v169, v169, v226
	ds_bpermute_b32 v178, v160, v166
	ds_bpermute_b32 v179, v160, v167
	ds_bpermute_b32 v180, v160, v168
	ds_bpermute_b32 v181, v160, v169
	s_waitcnt lgkmcnt(0)
	v_add_f32_e32 v166, v166, v178
	v_add_f32_e32 v167, v167, v179
	v_add_f32_e32 v168, v168, v180
	v_add_f32_e32 v169, v169, v181
	ds_bpermute_b32 v178, v161, v166
	ds_bpermute_b32 v179, v161, v167
	ds_bpermute_b32 v180, v161, v168
	ds_bpermute_b32 v181, v161, v169
	s_waitcnt lgkmcnt(0)
	v_add_f32_e32 v166, v166, v178
	v_add_f32_e32 v167, v167, v179
	v_add_f32_e32 v168, v168, v180
	v_add_f32_e32 v169, v169, v181
	ds_bpermute_b32 v178, v162, v166
	ds_bpermute_b32 v179, v162, v167
	ds_bpermute_b32 v180, v162, v168
	ds_bpermute_b32 v181, v162, v169
	s_waitcnt lgkmcnt(0)
	v_add_f32_e32 v166, v166, v178
	v_add_f32_e32 v167, v167, v179
	v_add_f32_e32 v168, v168, v180
	v_add_f32_e32 v169, v169, v181
	ds_bpermute_b32 v178, v163, v166
	ds_bpermute_b32 v179, v163, v167
	ds_bpermute_b32 v180, v163, v168
	ds_bpermute_b32 v181, v163, v169
	s_waitcnt lgkmcnt(0)
	v_add_f32_e32 v166, v166, v178
	v_add_f32_e32 v167, v167, v179
	v_add_f32_e32 v168, v168, v180
	v_add_f32_e32 v169, v169, v181
	ds_bpermute_b32 v178, v164, v166
	ds_bpermute_b32 v179, v164, v167
	ds_bpermute_b32 v180, v164, v168
	ds_bpermute_b32 v181, v164, v169
	s_waitcnt lgkmcnt(0)
	v_add_f32_e32 v166, v166, v178
	v_add_f32_e32 v167, v167, v179
	v_add_f32_e32 v168, v168, v180
	v_add_f32_e32 v169, v169, v181
	ds_bpermute_b32 v178, v165, v166
	ds_bpermute_b32 v179, v165, v167
	ds_bpermute_b32 v180, v165, v168
	ds_bpermute_b32 v181, v165, v169
	s_waitcnt lgkmcnt(0)
	v_add_f32_e32 v166, v166, v178
	v_add_f32_e32 v167, v167, v179
	v_add_f32_e32 v168, v168, v180
	v_add_f32_e32 v169, v169, v181
	v_mul_f32_e32 v166, 0x3a800000, v166
	v_mul_f32_e32 v167, 0x3a800000, v167
	v_mul_f32_e32 v168, 0x3a800000, v168
	v_mul_f32_e32 v169, 0x3a800000, v169
	v_mov_b32_e32 v174, 0
	v_sub_f32_e32 v0, v0, v166
	v_fmac_f32_e32 v174, v0, v0
	v_sub_f32_e32 v1, v1, v166
	v_fmac_f32_e32 v174, v1, v1
	v_sub_f32_e32 v2, v2, v166
	v_fmac_f32_e32 v174, v2, v2
	v_sub_f32_e32 v3, v3, v166
	v_fmac_f32_e32 v174, v3, v3
	v_sub_f32_e32 v4, v4, v166
	v_fmac_f32_e32 v174, v4, v4
	v_sub_f32_e32 v5, v5, v166
	v_fmac_f32_e32 v174, v5, v5
	v_sub_f32_e32 v6, v6, v166
	v_fmac_f32_e32 v174, v6, v6
	v_sub_f32_e32 v7, v7, v166
	v_fmac_f32_e32 v174, v7, v7
	v_sub_f32_e32 v8, v8, v166
	v_fmac_f32_e32 v174, v8, v8
	v_sub_f32_e32 v9, v9, v166
	v_fmac_f32_e32 v174, v9, v9
	v_sub_f32_e32 v10, v10, v166
	v_fmac_f32_e32 v174, v10, v10
	v_sub_f32_e32 v11, v11, v166
	v_fmac_f32_e32 v174, v11, v11
	v_sub_f32_e32 v12, v12, v166
	v_fmac_f32_e32 v174, v12, v12
	v_sub_f32_e32 v13, v13, v166
	v_fmac_f32_e32 v174, v13, v13
	v_sub_f32_e32 v14, v14, v166
	v_fmac_f32_e32 v174, v14, v14
	v_sub_f32_e32 v15, v15, v166
	v_fmac_f32_e32 v174, v15, v15
	v_mov_b32_e32 v175, 0
	v_sub_f32_e32 v16, v16, v167
	v_fmac_f32_e32 v175, v16, v16
	v_sub_f32_e32 v17, v17, v167
	v_fmac_f32_e32 v175, v17, v17
	v_sub_f32_e32 v18, v18, v167
	v_fmac_f32_e32 v175, v18, v18
	v_sub_f32_e32 v19, v19, v167
	v_fmac_f32_e32 v175, v19, v19
	v_sub_f32_e32 v20, v20, v167
	v_fmac_f32_e32 v175, v20, v20
	v_sub_f32_e32 v21, v21, v167
	v_fmac_f32_e32 v175, v21, v21
	v_sub_f32_e32 v22, v22, v167
	v_fmac_f32_e32 v175, v22, v22
	v_sub_f32_e32 v23, v23, v167
	v_fmac_f32_e32 v175, v23, v23
	v_sub_f32_e32 v24, v24, v167
	v_fmac_f32_e32 v175, v24, v24
	v_sub_f32_e32 v25, v25, v167
	v_fmac_f32_e32 v175, v25, v25
	v_sub_f32_e32 v26, v26, v167
	v_fmac_f32_e32 v175, v26, v26
	v_sub_f32_e32 v27, v27, v167
	v_fmac_f32_e32 v175, v27, v27
	v_sub_f32_e32 v28, v28, v167
	v_fmac_f32_e32 v175, v28, v28
	v_sub_f32_e32 v29, v29, v167
	v_fmac_f32_e32 v175, v29, v29
	v_sub_f32_e32 v30, v30, v167
	v_fmac_f32_e32 v175, v30, v30
	v_sub_f32_e32 v31, v31, v167
	v_fmac_f32_e32 v175, v31, v31
	v_mov_b32_e32 v176, 0
	v_sub_f32_e32 v32, v32, v168
	v_fmac_f32_e32 v176, v32, v32
	v_sub_f32_e32 v33, v33, v168
; DI unsigned pk2(float a, float b) { f32x2 v = {a, b}; bfx2 r = __builtin_convertvector(v, bfx2); return __builtin_bit_cast(unsigned, r); }
; template <int NR>
; DI void ln_rows(const Params& P, const LnSpec& sp, int row, int stride, int lane) {
;     ...
;     for (int k = 0; k < NR; ++k) {
;         s[k] *= (1.f / 1024.f); qv[k] = 0.f;
; #pragma unroll
;         for (int i = 0; i < 4; ++i)
; #pragma unroll
;             for (int j = 0; j < 4; ++j) { const float d = v[k][i][j] - s[k]; qv[k] += d * d; }
;     }
; #pragma unroll
;     for (int o = 32; o >= 1; o >>= 1)
; #pragma unroll
;         for (int k = 0; k < NR; ++k) qv[k] += __shfl_xor(qv[k], o);
; #pragma unroll
;     for (int k = 0; k < NR; ++k) {
;         const int r = row + k * stride;
;         const float mu = s[k], rstd = rsqrtf(qv[k] * (1.f / 1024.f) + 1e-6f);
;         const int sidx = r < RL ? (r >> 13) : 4;
;         const float* sh = MOD + (size_t)(sp.lnext * 5 + sidx) * 9216 + sp.mshift * 1024; const float* scl = sh + 1024;
;         float* xp = X + (size_t)r * 1024;
; #pragma unroll
;         for (int i = 0; i < 4; ++i) {
;             const int c = (i * 64 + lane) * 4;
;             const f32x4 gg = *(const f32x4*)(g + c), b4 = *(const f32x4*)(bb + c);
;             f32x4 y;
; #pragma unroll
;             for (int j = 0; j < 4; ++j) y[j] = (v[k][i][j] - mu) * rstd * gg[j] + b4[j];
;             if (sp.final_) { __builtin_nontemporal_store(y, (f32x4*)(P.out + (size_t)r * 1024 + c)); }
;             else {
;                 __builtin_nontemporal_store(y, (f32x4*)(xp + c));
;                 const f32x4 a = *(const f32x4*)(sh + c), sg = *(const f32x4*)(scl + c);
;                 u32x2 w; w.x = pk2(y[0] * (1.f + sg[0]) + a[0], y[1] * (1.f + sg[1]) + a[1]); w.y = pk2(y[2] * (1.f + sg[2]) + a[2], y[3] * (1.f + sg[3]) + a[3]);
;                 *(u32x2*)(XM + (size_t)r * 1024 + c) = w;
	v_fmac_f32_e32 v176, v33, v33
	v_sub_f32_e32 v34, v34, v168
	v_fmac_f32_e32 v176, v34, v34
	v_sub_f32_e32 v35, v35, v168
	v_fmac_f32_e32 v176, v35, v35
	v_sub_f32_e32 v36, v36, v168
	v_fmac_f32_e32 v176, v36, v36
	v_sub_f32_e32 v37, v37, v168
	v_fmac_f32_e32 v176, v37, v37
	v_sub_f32_e32 v38, v38, v168
	v_fmac_f32_e32 v176, v38, v38
	v_sub_f32_e32 v39, v39, v168
	v_fmac_f32_e32 v176, v39, v39
	v_sub_f32_e32 v40, v40, v168
	v_fmac_f32_e32 v176, v40, v40
	v_sub_f32_e32 v41, v41, v168
	v_fmac_f32_e32 v176, v41, v41
	v_sub_f32_e32 v42, v42, v168
	v_fmac_f32_e32 v176, v42, v42
	v_sub_f32_e32 v43, v43, v168
	v_fmac_f32_e32 v176, v43, v43
	v_sub_f32_e32 v44, v44, v168
	v_fmac_f32_e32 v176, v44, v44
	v_sub_f32_e32 v45, v45, v168
	v_fmac_f32_e32 v176, v45, v45
	v_sub_f32_e32 v46, v46, v168
	v_fmac_f32_e32 v176, v46, v46
	v_sub_f32_e32 v47, v47, v168
	v_fmac_f32_e32 v176, v47, v47
	v_mov_b32_e32 v177, 0
	v_sub_f32_e32 v48, v48, v169
	v_fmac_f32_e32 v177, v48, v48
	v_sub_f32_e32 v49, v49, v169
	v_fmac_f32_e32 v177, v49, v49
	v_sub_f32_e32 v50, v50, v169
	v_fmac_f32_e32 v177, v50, v50
	v_sub_f32_e32 v51, v51, v169
	v_fmac_f32_e32 v177, v51, v51
	v_sub_f32_e32 v52, v52, v169
	v_fmac_f32_e32 v177, v52, v52
	v_sub_f32_e32 v53, v53, v169
	v_fmac_f32_e32 v177, v53, v53
	v_sub_f32_e32 v54, v54, v169
	v_fmac_f32_e32 v177, v54, v54
	v_sub_f32_e32 v55, v55, v169
	v_fmac_f32_e32 v177, v55, v55
	v_sub_f32_e32 v56, v56, v169
	v_fmac_f32_e32 v177, v56, v56
	v_sub_f32_e32 v57, v57, v169
	v_fmac_f32_e32 v177, v57, v57
	v_sub_f32_e32 v58, v58, v169
	v_fmac_f32_e32 v177, v58, v58
	v_sub_f32_e32 v59, v59, v169
	v_fmac_f32_e32 v177, v59, v59
	v_sub_f32_e32 v60, v60, v169
	v_fmac_f32_e32 v177, v60, v60
	v_sub_f32_e32 v61, v61, v169
	v_fmac_f32_e32 v177, v61, v61
	v_sub_f32_e32 v62, v62, v169
	v_fmac_f32_e32 v177, v62, v62
	v_sub_f32_e32 v63, v63, v169
	v_fmac_f32_e32 v177, v63, v63
	ds_bpermute_b32 v178, v160, v174
	ds_bpermute_b32 v179, v160, v175
	ds_bpermute_b32 v180, v160, v176
	ds_bpermute_b32 v181, v160, v177
	s_waitcnt lgkmcnt(0)
	v_add_f32_e32 v174, v174, v178
	v_add_f32_e32 v175, v175, v179
	v_add_f32_e32 v176, v176, v180
	v_add_f32_e32 v177, v177, v181
	ds_bpermute_b32 v178, v161, v174
	ds_bpermute_b32 v179, v161, v175
	ds_bpermute_b32 v180, v161, v176
	ds_bpermute_b32 v181, v161, v177
	s_waitcnt lgkmcnt(0)
	v_add_f32_e32 v174, v174, v178
	v_add_f32_e32 v175, v175, v179
	v_add_f32_e32 v176, v176, v180
	v_add_f32_e32 v177, v177, v181
	ds_bpermute_b32 v178, v162, v174
	ds_bpermute_b32 v179, v162, v175
	ds_bpermute_b32 v180, v162, v176
	ds_bpermute_b32 v181, v162, v177
	s_waitcnt lgkmcnt(0)
	v_add_f32_e32 v174, v174, v178
	v_add_f32_e32 v175, v175, v179
	v_add_f32_e32 v176, v176, v180
	v_add_f32_e32 v177, v177, v181
	ds_bpermute_b32 v178, v163, v174
	ds_bpermute_b32 v179, v163, v175
	ds_bpermute_b32 v180, v163, v176
	ds_bpermute_b32 v181, v163, v177
	s_waitcnt lgkmcnt(0)
	v_add_f32_e32 v174, v174, v178
	v_add_f32_e32 v175, v175, v179
	v_add_f32_e32 v176, v176, v180
	v_add_f32_e32 v177, v177, v181
	ds_bpermute_b32 v178, v164, v174
	ds_bpermute_b32 v179, v164, v175
	ds_bpermute_b32 v180, v164, v176
	ds_bpermute_b32 v181, v164, v177
	s_waitcnt lgkmcnt(0)
	v_add_f32_e32 v174, v174, v178
	v_add_f32_e32 v175, v175, v179
	v_add_f32_e32 v176, v176, v180
	v_add_f32_e32 v177, v177, v181
	ds_bpermute_b32 v178, v165, v174
	ds_bpermute_b32 v179, v165, v175
	ds_bpermute_b32 v180, v165, v176
	ds_bpermute_b32 v181, v165, v177
	s_waitcnt lgkmcnt(0)
	v_add_f32_e32 v174, v174, v178
	v_add_f32_e32 v175, v175, v179
	v_add_f32_e32 v176, v176, v180
	v_add_f32_e32 v177, v177, v181
	v_fmaak_f32 v174, v228, v174, 0x358637bd
	v_fmaak_f32 v175, v228, v175, 0x358637bd
	v_fmaak_f32 v176, v228, v176, 0x358637bd
	v_fmaak_f32 v177, v228, v177, 0x358637bd
	v_rsq_f32_e32 v182, v174
	v_rsq_f32_e32 v183, v175
	v_rsq_f32_e32 v184, v176
	v_rsq_f32_e32 v185, v177
	s_waitcnt vmcnt(0)
	s_cmp_eq_u32 s18, 1
	s_cbranch_scc1 .Lmy_ln1_final
	v_add_f32_e32 v144, 1.0, v144
	v_add_f32_e32 v145, 1.0, v145
	v_add_f32_e32 v146, 1.0, v146
	v_add_f32_e32 v147, 1.0, v147
	v_add_f32_e32 v148, 1.0, v148
	v_add_f32_e32 v149, 1.0, v149
	v_add_f32_e32 v150, 1.0, v150
	v_add_f32_e32 v151, 1.0, v151
	v_add_f32_e32 v152, 1.0, v152
	v_add_f32_e32 v153, 1.0, v153
	v_add_f32_e32 v154, 1.0, v154
	v_add_f32_e32 v155, 1.0, v155
	v_add_f32_e32 v156, 1.0, v156
	v_add_f32_e32 v157, 1.0, v157
	v_add_f32_e32 v158, 1.0, v158
	v_add_f32_e32 v159, 1.0, v159
	v_mul_f32_e32 v0, v0, v182
	v_mul_f32_e32 v1, v1, v182
	v_mul_f32_e32 v2, v2, v182
	v_mul_f32_e32 v3, v3, v182
	v_fma_f32 v0, v0, v96, v112
	v_fma_f32 v1, v1, v97, v113
	v_fma_f32 v2, v2, v98, v114
	v_fma_f32 v3, v3, v99, v115
	global_store_dwordx4 v218, v[0:3], s[94:95] nt
	v_fma_f32 v224, v0, v144, v128
	v_fma_f32 v225, v1, v145, v129
	v_fma_f32 v226, v2, v146, v130
	v_fma_f32 v227, v3, v147, v131
	v_cvt_pk_bf16_f32 v232, v224, v225
	v_cvt_pk_bf16_f32 v233, v226, v227
	global_store_dwordx2 v222, v[232:233], s[94:95]
	v_mul_f32_e32 v4, v4, v182
	v_mul_f32_e32 v5, v5, v182
	v_mul_f32_e32 v6, v6, v182
	v_mul_f32_e32 v7, v7, v182
	v_fma_f32 v4, v4, v100, v116
	v_fma_f32 v5, v5, v101, v117
	v_fma_f32 v6, v6, v102, v118
	v_fma_f32 v7, v7, v103, v119
	global_store_dwordx4 v218, v[4:7], s[94:95] offset:1024 nt
	v_fma_f32 v224, v4, v148, v132
	v_fma_f32 v225, v5, v149, v133
	v_fma_f32 v226, v6, v150, v134
	v_fma_f32 v227, v7, v151, v135
	v_cvt_pk_bf16_f32 v232, v224, v225
	v_cvt_pk_bf16_f32 v233, v226, v227
	global_store_dwordx2 v222, v[232:233], s[94:95] offset:512
	v_mul_f32_e32 v8, v8, v182
	v_mul_f32_e32 v9, v9, v182
	v_mul_f32_e32 v10, v10, v182
	v_mul_f32_e32 v11, v11, v182
; DI unsigned pk2(float a, float b) { f32x2 v = {a, b}; bfx2 r = __builtin_convertvector(v, bfx2); return __builtin_bit_cast(unsigned, r); }
; template <int NR>
; DI void ln_rows(const Params& P, const LnSpec& sp, int row, int stride, int lane) {
;     ...
;     for (int k = 0; k < NR; ++k) {
;         const int r = row + k * stride;
;         const float mu = s[k], rstd = rsqrtf(qv[k] * (1.f / 1024.f) + 1e-6f);
;         const int sidx = r < RL ? (r >> 13) : 4;
;         const float* sh = MOD + (size_t)(sp.lnext * 5 + sidx) * 9216 + sp.mshift * 1024; const float* scl = sh + 1024;
;         float* xp = X + (size_t)r * 1024;
; #pragma unroll
;         for (int i = 0; i < 4; ++i) {
;             const int c = (i * 64 + lane) * 4;
;             const f32x4 gg = *(const f32x4*)(g + c), b4 = *(const f32x4*)(bb + c);
;             f32x4 y;
; #pragma unroll
;             for (int j = 0; j < 4; ++j) y[j] = (v[k][i][j] - mu) * rstd * gg[j] + b4[j];
;             if (sp.final_) { __builtin_nontemporal_store(y, (f32x4*)(P.out + (size_t)r * 1024 + c)); }
;             else {
;                 __builtin_nontemporal_store(y, (f32x4*)(xp + c));
;                 const f32x4 a = *(const f32x4*)(sh + c), sg = *(const f32x4*)(scl + c);
;                 u32x2 w; w.x = pk2(y[0] * (1.f + sg[0]) + a[0], y[1] * (1.f + sg[1]) + a[1]); w.y = pk2(y[2] * (1.f + sg[2]) + a[2], y[3] * (1.f + sg[3]) + a[3]);
;                 *(u32x2*)(XM + (size_t)r * 1024 + c) = w;
	v_fma_f32 v8, v8, v104, v120
	v_fma_f32 v9, v9, v105, v121
	v_fma_f32 v10, v10, v106, v122
	v_fma_f32 v11, v11, v107, v123
	global_store_dwordx4 v218, v[8:11], s[94:95] offset:2048 nt
	v_fma_f32 v224, v8, v152, v136
	v_fma_f32 v225, v9, v153, v137
	v_fma_f32 v226, v10, v154, v138
	v_fma_f32 v227, v11, v155, v139
	v_cvt_pk_bf16_f32 v232, v224, v225
	v_cvt_pk_bf16_f32 v233, v226, v227
	global_store_dwordx2 v222, v[232:233], s[94:95] offset:1024
	v_mul_f32_e32 v12, v12, v182
	v_mul_f32_e32 v13, v13, v182
	v_mul_f32_e32 v14, v14, v182
	v_mul_f32_e32 v15, v15, v182
	v_fma_f32 v12, v12, v108, v124
	v_fma_f32 v13, v13, v109, v125
	v_fma_f32 v14, v14, v110, v126
	v_fma_f32 v15, v15, v111, v127
	global_store_dwordx4 v218, v[12:15], s[94:95] offset:3072 nt
	v_fma_f32 v224, v12, v156, v140
	v_fma_f32 v225, v13, v157, v141
	v_fma_f32 v226, v14, v158, v142
	v_fma_f32 v227, v15, v159, v143
	v_cvt_pk_bf16_f32 v232, v224, v225
	v_cvt_pk_bf16_f32 v233, v226, v227
	global_store_dwordx2 v222, v[232:233], s[94:95] offset:1536
	v_mul_f32_e32 v16, v16, v183
	v_mul_f32_e32 v17, v17, v183
	v_mul_f32_e32 v18, v18, v183
	v_mul_f32_e32 v19, v19, v183
	v_fma_f32 v16, v16, v96, v112
	v_fma_f32 v17, v17, v97, v113
	v_fma_f32 v18, v18, v98, v114
	v_fma_f32 v19, v19, v99, v115
	global_store_dwordx4 v219, v[16:19], s[94:95] nt
	v_fma_f32 v224, v16, v144, v128
	v_fma_f32 v225, v17, v145, v129
	v_fma_f32 v226, v18, v146, v130
	v_fma_f32 v227, v19, v147, v131
	v_cvt_pk_bf16_f32 v232, v224, v225
	v_cvt_pk_bf16_f32 v233, v226, v227
	global_store_dwordx2 v222, v[232:233], s[94:95] offset:2048
	v_mul_f32_e32 v20, v20, v183
	v_mul_f32_e32 v21, v21, v183
	v_mul_f32_e32 v22, v22, v183
	v_mul_f32_e32 v23, v23, v183
	v_fma_f32 v20, v20, v100, v116
	v_fma_f32 v21, v21, v101, v117
	v_fma_f32 v22, v22, v102, v118
	v_fma_f32 v23, v23, v103, v119
	global_store_dwordx4 v219, v[20:23], s[94:95] offset:1024 nt
	v_fma_f32 v224, v20, v148, v132
	v_fma_f32 v225, v21, v149, v133
	v_fma_f32 v226, v22, v150, v134
	v_fma_f32 v227, v23, v151, v135
	v_cvt_pk_bf16_f32 v232, v224, v225
	v_cvt_pk_bf16_f32 v233, v226, v227
	global_store_dwordx2 v222, v[232:233], s[94:95] offset:2560
	v_mul_f32_e32 v24, v24, v183
	v_mul_f32_e32 v25, v25, v183
	v_mul_f32_e32 v26, v26, v183
	v_mul_f32_e32 v27, v27, v183
	v_fma_f32 v24, v24, v104, v120
	v_fma_f32 v25, v25, v105, v121
	v_fma_f32 v26, v26, v106, v122
	v_fma_f32 v27, v27, v107, v123
	global_store_dwordx4 v219, v[24:27], s[94:95] offset:2048 nt
	v_fma_f32 v224, v24, v152, v136
	v_fma_f32 v225, v25, v153, v137
	v_fma_f32 v226, v26, v154, v138
	v_fma_f32 v227, v27, v155, v139
	v_cvt_pk_bf16_f32 v232, v224, v225
	v_cvt_pk_bf16_f32 v233, v226, v227
	global_store_dwordx2 v222, v[232:233], s[94:95] offset:3072
	v_mul_f32_e32 v28, v28, v183
	v_mul_f32_e32 v29, v29, v183
	v_mul_f32_e32 v30, v30, v183
	v_mul_f32_e32 v31, v31, v183
	v_fma_f32 v28, v28, v108, v124
	v_fma_f32 v29, v29, v109, v125
	v_fma_f32 v30, v30, v110, v126
	v_fma_f32 v31, v31, v111, v127
	global_store_dwordx4 v219, v[28:31], s[94:95] offset:3072 nt
	v_fma_f32 v224, v28, v156, v140
	v_fma_f32 v225, v29, v157, v141
	v_fma_f32 v226, v30, v158, v142
	v_fma_f32 v227, v31, v159, v143
	v_cvt_pk_bf16_f32 v232, v224, v225
	v_cvt_pk_bf16_f32 v233, v226, v227
	global_store_dwordx2 v222, v[232:233], s[94:95] offset:3584
	v_mul_f32_e32 v32, v32, v184
	v_mul_f32_e32 v33, v33, v184
	v_mul_f32_e32 v34, v34, v184
	v_mul_f32_e32 v35, v35, v184
	v_fma_f32 v32, v32, v96, v112
	v_fma_f32 v33, v33, v97, v113
	v_fma_f32 v34, v34, v98, v114
	v_fma_f32 v35, v35, v99, v115
	global_store_dwordx4 v220, v[32:35], s[94:95] nt
	v_fma_f32 v224, v32, v144, v128
	v_fma_f32 v225, v33, v145, v129
	v_fma_f32 v226, v34, v146, v130
	v_fma_f32 v227, v35, v147, v131
	v_cvt_pk_bf16_f32 v232, v224, v225
	v_cvt_pk_bf16_f32 v233, v226, v227
	global_store_dwordx2 v223, v[232:233], s[94:95]
	v_mul_f32_e32 v36, v36, v184
	v_mul_f32_e32 v37, v37, v184
	v_mul_f32_e32 v38, v38, v184
	v_mul_f32_e32 v39, v39, v184
	v_fma_f32 v36, v36, v100, v116
	v_fma_f32 v37, v37, v101, v117
	v_fma_f32 v38, v38, v102, v118
	v_fma_f32 v39, v39, v103, v119
	global_store_dwordx4 v220, v[36:39], s[94:95] offset:1024 nt
	v_fma_f32 v224, v36, v148, v132
	v_fma_f32 v225, v37, v149, v133
	v_fma_f32 v226, v38, v150, v134
	v_fma_f32 v227, v39, v151, v135
	v_cvt_pk_bf16_f32 v232, v224, v225
	v_cvt_pk_bf16_f32 v233, v226, v227
	global_store_dwordx2 v223, v[232:233], s[94:95] offset:512
	v_mul_f32_e32 v40, v40, v184
	v_mul_f32_e32 v41, v41, v184
	v_mul_f32_e32 v42, v42, v184
	v_mul_f32_e32 v43, v43, v184
	v_fma_f32 v40, v40, v104, v120
	v_fma_f32 v41, v41, v105, v121
	v_fma_f32 v42, v42, v106, v122
	v_fma_f32 v43, v43, v107, v123
	global_store_dwordx4 v220, v[40:43], s[94:95] offset:2048 nt
	v_fma_f32 v224, v40, v152, v136
	v_fma_f32 v225, v41, v153, v137
	v_fma_f32 v226, v42, v154, v138
	v_fma_f32 v227, v43, v155, v139
	v_cvt_pk_bf16_f32 v232, v224, v225
	v_cvt_pk_bf16_f32 v233, v226, v227
	global_store_dwordx2 v223, v[232:233], s[94:95] offset:1024
	v_mul_f32_e32 v44, v44, v184
	v_mul_f32_e32 v45, v45, v184
	v_mul_f32_e32 v46, v46, v184
	v_mul_f32_e32 v47, v47, v184
	v_fma_f32 v44, v44, v108, v124
	v_fma_f32 v45, v45, v109, v125
	v_fma_f32 v46, v46, v110, v126
	v_fma_f32 v47, v47, v111, v127
	global_store_dwordx4 v220, v[44:47], s[94:95] offset:3072 nt
	v_fma_f32 v224, v44, v156, v140
	v_fma_f32 v225, v45, v157, v141
	v_fma_f32 v226, v46, v158, v142
	v_fma_f32 v227, v47, v159, v143
	v_cvt_pk_bf16_f32 v232, v224, v225
	v_cvt_pk_bf16_f32 v233, v226, v227
	global_store_dwordx2 v223, v[232:233], s[94:95] offset:1536
	v_mul_f32_e32 v48, v48, v185
	v_mul_f32_e32 v49, v49, v185
; DI unsigned pk2(float a, float b) { f32x2 v = {a, b}; bfx2 r = __builtin_convertvector(v, bfx2); return __builtin_bit_cast(unsigned, r); }
; template <int NR>
; DI void ln_rows(const Params& P, const LnSpec& sp, int row, int stride, int lane) {
;     ...
;     for (int k = 0; k < NR; ++k) {
;         const int r = row + k * stride;
;         const float mu = s[k], rstd = rsqrtf(qv[k] * (1.f / 1024.f) + 1e-6f);
;         const int sidx = r < RL ? (r >> 13) : 4;
;         const float* sh = MOD + (size_t)(sp.lnext * 5 + sidx) * 9216 + sp.mshift * 1024; const float* scl = sh + 1024;
;         float* xp = X + (size_t)r * 1024;
; #pragma unroll
;         for (int i = 0; i < 4; ++i) {
;             const int c = (i * 64 + lane) * 4;
;             const f32x4 gg = *(const f32x4*)(g + c), b4 = *(const f32x4*)(bb + c);
;             f32x4 y;
; #pragma unroll
;             for (int j = 0; j < 4; ++j) y[j] = (v[k][i][j] - mu) * rstd * gg[j] + b4[j];
;             if (sp.final_) { __builtin_nontemporal_store(y, (f32x4*)(P.out + (size_t)r * 1024 + c)); }
;             else {
;                 __builtin_nontemporal_store(y, (f32x4*)(xp + c));
;                 const f32x4 a = *(const f32x4*)(sh + c), sg = *(const f32x4*)(scl + c);
;                 u32x2 w; w.x = pk2(y[0] * (1.f + sg[0]) + a[0], y[1] * (1.f + sg[1]) + a[1]); w.y = pk2(y[2] * (1.f + sg[2]) + a[2], y[3] * (1.f + sg[3]) + a[3]);
;                 *(u32x2*)(XM + (size_t)r * 1024 + c) = w;
	v_mul_f32_e32 v50, v50, v185
	v_mul_f32_e32 v51, v51, v185
	v_fma_f32 v48, v48, v96, v112
	v_fma_f32 v49, v49, v97, v113
	v_fma_f32 v50, v50, v98, v114
	v_fma_f32 v51, v51, v99, v115
	global_store_dwordx4 v221, v[48:51], s[94:95] nt
	v_fma_f32 v224, v48, v144, v128
	v_fma_f32 v225, v49, v145, v129
	v_fma_f32 v226, v50, v146, v130
	v_fma_f32 v227, v51, v147, v131
	v_cvt_pk_bf16_f32 v232, v224, v225
	v_cvt_pk_bf16_f32 v233, v226, v227
	global_store_dwordx2 v223, v[232:233], s[94:95] offset:2048
	v_mul_f32_e32 v52, v52, v185
	v_mul_f32_e32 v53, v53, v185
	v_mul_f32_e32 v54, v54, v185
	v_mul_f32_e32 v55, v55, v185
	v_fma_f32 v52, v52, v100, v116
	v_fma_f32 v53, v53, v101, v117
	v_fma_f32 v54, v54, v102, v118
	v_fma_f32 v55, v55, v103, v119
	global_store_dwordx4 v221, v[52:55], s[94:95] offset:1024 nt
	v_fma_f32 v224, v52, v148, v132
	v_fma_f32 v225, v53, v149, v133
	v_fma_f32 v226, v54, v150, v134
	v_fma_f32 v227, v55, v151, v135
	v_cvt_pk_bf16_f32 v232, v224, v225
	v_cvt_pk_bf16_f32 v233, v226, v227
	global_store_dwordx2 v223, v[232:233], s[94:95] offset:2560
	v_mul_f32_e32 v56, v56, v185
	v_mul_f32_e32 v57, v57, v185
	v_mul_f32_e32 v58, v58, v185
	v_mul_f32_e32 v59, v59, v185
	v_fma_f32 v56, v56, v104, v120
	v_fma_f32 v57, v57, v105, v121
	v_fma_f32 v58, v58, v106, v122
	v_fma_f32 v59, v59, v107, v123
	global_store_dwordx4 v221, v[56:59], s[94:95] offset:2048 nt
	v_fma_f32 v224, v56, v152, v136
	v_fma_f32 v225, v57, v153, v137
	v_fma_f32 v226, v58, v154, v138
	v_fma_f32 v227, v59, v155, v139
	v_cvt_pk_bf16_f32 v232, v224, v225
	v_cvt_pk_bf16_f32 v233, v226, v227
	global_store_dwordx2 v223, v[232:233], s[94:95] offset:3072
	v_mul_f32_e32 v60, v60, v185
	v_mul_f32_e32 v61, v61, v185
	v_mul_f32_e32 v62, v62, v185
	v_mul_f32_e32 v63, v63, v185
	v_fma_f32 v60, v60, v108, v124
	v_fma_f32 v61, v61, v109, v125
	v_fma_f32 v62, v62, v110, v126
	v_fma_f32 v63, v63, v111, v127
	global_store_dwordx4 v221, v[60:63], s[94:95] offset:3072 nt
	v_fma_f32 v224, v60, v156, v140
	v_fma_f32 v225, v61, v157, v141
	v_fma_f32 v226, v62, v158, v142
	v_fma_f32 v227, v63, v159, v143
	v_cvt_pk_bf16_f32 v232, v224, v225
	v_cvt_pk_bf16_f32 v233, v226, v227
	global_store_dwordx2 v223, v[232:233], s[94:95] offset:3584
	s_branch .Lmy_ln1_next
.Lmy_ln1_final:
	v_mul_f32_e32 v0, v0, v182
	v_mul_f32_e32 v1, v1, v182
	v_mul_f32_e32 v2, v2, v182
	v_mul_f32_e32 v3, v3, v182
	v_fma_f32 v0, v0, v96, v112
	v_fma_f32 v1, v1, v97, v113
	v_fma_f32 v2, v2, v98, v114
	v_fma_f32 v3, v3, v99, v115
	global_store_dwordx4 v218, v[0:3], s[92:93] nt
	v_mul_f32_e32 v4, v4, v182
	v_mul_f32_e32 v5, v5, v182
	v_mul_f32_e32 v6, v6, v182
	v_mul_f32_e32 v7, v7, v182
	v_fma_f32 v4, v4, v100, v116
	v_fma_f32 v5, v5, v101, v117
	v_fma_f32 v6, v6, v102, v118
	v_fma_f32 v7, v7, v103, v119
	global_store_dwordx4 v218, v[4:7], s[92:93] offset:1024 nt
	v_mul_f32_e32 v8, v8, v182
	v_mul_f32_e32 v9, v9, v182
	v_mul_f32_e32 v10, v10, v182
	v_mul_f32_e32 v11, v11, v182
	v_fma_f32 v8, v8, v104, v120
	v_fma_f32 v9, v9, v105, v121
	v_fma_f32 v10, v10, v106, v122
	v_fma_f32 v11, v11, v107, v123
	global_store_dwordx4 v218, v[8:11], s[92:93] offset:2048 nt
	v_mul_f32_e32 v12, v12, v182
	v_mul_f32_e32 v13, v13, v182
	v_mul_f32_e32 v14, v14, v182
	v_mul_f32_e32 v15, v15, v182
	v_fma_f32 v12, v12, v108, v124
	v_fma_f32 v13, v13, v109, v125
	v_fma_f32 v14, v14, v110, v126
	v_fma_f32 v15, v15, v111, v127
	global_store_dwordx4 v218, v[12:15], s[92:93] offset:3072 nt
	v_mul_f32_e32 v16, v16, v183
	v_mul_f32_e32 v17, v17, v183
	v_mul_f32_e32 v18, v18, v183
	v_mul_f32_e32 v19, v19, v183
	v_fma_f32 v16, v16, v96, v112
	v_fma_f32 v17, v17, v97, v113
	v_fma_f32 v18, v18, v98, v114
	v_fma_f32 v19, v19, v99, v115
	global_store_dwordx4 v219, v[16:19], s[92:93] nt
	v_mul_f32_e32 v20, v20, v183
	v_mul_f32_e32 v21, v21, v183
	v_mul_f32_e32 v22, v22, v183
	v_mul_f32_e32 v23, v23, v183
	v_fma_f32 v20, v20, v100, v116
	v_fma_f32 v21, v21, v101, v117
	v_fma_f32 v22, v22, v102, v118
	v_fma_f32 v23, v23, v103, v119
	global_store_dwordx4 v219, v[20:23], s[92:93] offset:1024 nt
	v_mul_f32_e32 v24, v24, v183
	v_mul_f32_e32 v25, v25, v183
	v_mul_f32_e32 v26, v26, v183
	v_mul_f32_e32 v27, v27, v183
	v_fma_f32 v24, v24, v104, v120
	v_fma_f32 v25, v25, v105, v121
	v_fma_f32 v26, v26, v106, v122
	v_fma_f32 v27, v27, v107, v123
	global_store_dwordx4 v219, v[24:27], s[92:93] offset:2048 nt
	v_mul_f32_e32 v28, v28, v183
	v_mul_f32_e32 v29, v29, v183
	v_mul_f32_e32 v30, v30, v183
	v_mul_f32_e32 v31, v31, v183
	v_fma_f32 v28, v28, v108, v124
	v_fma_f32 v29, v29, v109, v125
	v_fma_f32 v30, v30, v110, v126
	v_fma_f32 v31, v31, v111, v127
	global_store_dwordx4 v219, v[28:31], s[92:93] offset:3072 nt
	v_mul_f32_e32 v32, v32, v184
	v_mul_f32_e32 v33, v33, v184
	v_mul_f32_e32 v34, v34, v184
	v_mul_f32_e32 v35, v35, v184
	v_fma_f32 v32, v32, v96, v112
	v_fma_f32 v33, v33, v97, v113
; DI int ltid() { int t = threadIdx.x; asm volatile("" : "+v"(t)); return t; }
; DI int lbid() { int t = blockIdx.x; asm volatile("" : "+s"(t)); return t; }
; DI unsigned pk2(float a, float b) { f32x2 v = {a, b}; bfx2 r = __builtin_convertvector(v, bfx2); return __builtin_bit_cast(unsigned, r); }
; template <int NR>
; DI void ln_rows(const Params& P, const LnSpec& sp, int row, int stride, int lane) {
;     ...
;     for (int k = 0; k < NR; ++k) {
;         const int r = row + k * stride;
;         const float mu = s[k], rstd = rsqrtf(qv[k] * (1.f / 1024.f) + 1e-6f);
;         const int sidx = r < RL ? (r >> 13) : 4;
;         const float* sh = MOD + (size_t)(sp.lnext * 5 + sidx) * 9216 + sp.mshift * 1024; const float* scl = sh + 1024;
;         float* xp = X + (size_t)r * 1024;
; #pragma unroll
;         for (int i = 0; i < 4; ++i) {
;             const int c = (i * 64 + lane) * 4;
;             const f32x4 gg = *(const f32x4*)(g + c), b4 = *(const f32x4*)(bb + c);
;             f32x4 y;
; #pragma unroll
;             for (int j = 0; j < 4; ++j) y[j] = (v[k][i][j] - mu) * rstd * gg[j] + b4[j];
;             if (sp.final_) { __builtin_nontemporal_store(y, (f32x4*)(P.out + (size_t)r * 1024 + c)); }
;             else {
;                 __builtin_nontemporal_store(y, (f32x4*)(xp + c));
;                 const f32x4 a = *(const f32x4*)(sh + c), sg = *(const f32x4*)(scl + c);
;                 u32x2 w; w.x = pk2(y[0] * (1.f + sg[0]) + a[0], y[1] * (1.f + sg[1]) + a[1]); w.y = pk2(y[2] * (1.f + sg[2]) + a[2], y[3] * (1.f + sg[3]) + a[3]);
;                 *(u32x2*)(XM + (size_t)r * 1024 + c) = w;
;             }
;         }
;     }
; }
; DI void phase_ln(const Params& P, int l, int which, int lnext, int mshift, bool final_, bool lat_only, const bf16_t* Y, bool first) {
;     float* X = (float*)(P.ws + OFF_X);
;     const LnSpec sp{l, which, lnext, mshift, final_, nullptr, Y, first ? P.in[0] : X, first ? P.in[2] : X + (size_t)RL * 1024};
;     const int lane = ltid() & 63, wave = ltid() >> 6;
;     const int nq = ((final_ || lat_only) ? RL : RT) / 4;
;     for (int q = lbid() * NWAVE + wave; q < nq; q += gridDim.x * NWAVE) ln_rows<4>(P, sp, 4 * q, 1, lane);
	v_fma_f32 v34, v34, v98, v114
	v_fma_f32 v35, v35, v99, v115
	global_store_dwordx4 v220, v[32:35], s[92:93] nt
	v_mul_f32_e32 v36, v36, v184
	v_mul_f32_e32 v37, v37, v184
	v_mul_f32_e32 v38, v38, v184
	v_mul_f32_e32 v39, v39, v184
	v_fma_f32 v36, v36, v100, v116
	v_fma_f32 v37, v37, v101, v117
	v_fma_f32 v38, v38, v102, v118
	v_fma_f32 v39, v39, v103, v119
	global_store_dwordx4 v220, v[36:39], s[92:93] offset:1024 nt
	v_mul_f32_e32 v40, v40, v184
	v_mul_f32_e32 v41, v41, v184
	v_mul_f32_e32 v42, v42, v184
	v_mul_f32_e32 v43, v43, v184
	v_fma_f32 v40, v40, v104, v120
	v_fma_f32 v41, v41, v105, v121
	v_fma_f32 v42, v42, v106, v122
	v_fma_f32 v43, v43, v107, v123
	global_store_dwordx4 v220, v[40:43], s[92:93] offset:2048 nt
	v_mul_f32_e32 v44, v44, v184
	v_mul_f32_e32 v45, v45, v184
	v_mul_f32_e32 v46, v46, v184
	v_mul_f32_e32 v47, v47, v184
	v_fma_f32 v44, v44, v108, v124
	v_fma_f32 v45, v45, v109, v125
	v_fma_f32 v46, v46, v110, v126
	v_fma_f32 v47, v47, v111, v127
	global_store_dwordx4 v220, v[44:47], s[92:93] offset:3072 nt
	v_mul_f32_e32 v48, v48, v185
	v_mul_f32_e32 v49, v49, v185
	v_mul_f32_e32 v50, v50, v185
	v_mul_f32_e32 v51, v51, v185
	v_fma_f32 v48, v48, v96, v112
	v_fma_f32 v49, v49, v97, v113
	v_fma_f32 v50, v50, v98, v114
	v_fma_f32 v51, v51, v99, v115
	global_store_dwordx4 v221, v[48:51], s[92:93] nt
	v_mul_f32_e32 v52, v52, v185
	v_mul_f32_e32 v53, v53, v185
	v_mul_f32_e32 v54, v54, v185
	v_mul_f32_e32 v55, v55, v185
	v_fma_f32 v52, v52, v100, v116
	v_fma_f32 v53, v53, v101, v117
	v_fma_f32 v54, v54, v102, v118
	v_fma_f32 v55, v55, v103, v119
	global_store_dwordx4 v221, v[52:55], s[92:93] offset:1024 nt
	v_mul_f32_e32 v56, v56, v185
	v_mul_f32_e32 v57, v57, v185
	v_mul_f32_e32 v58, v58, v185
	v_mul_f32_e32 v59, v59, v185
	v_fma_f32 v56, v56, v104, v120
	v_fma_f32 v57, v57, v105, v121
	v_fma_f32 v58, v58, v106, v122
	v_fma_f32 v59, v59, v107, v123
	global_store_dwordx4 v221, v[56:59], s[92:93] offset:2048 nt
	v_mul_f32_e32 v60, v60, v185
	v_mul_f32_e32 v61, v61, v185
	v_mul_f32_e32 v62, v62, v185
	v_mul_f32_e32 v63, v63, v185
	v_fma_f32 v60, v60, v108, v124
	v_fma_f32 v61, v61, v109, v125
	v_fma_f32 v62, v62, v110, v126
	v_fma_f32 v63, v63, v111, v127
	global_store_dwordx4 v221, v[60:63], s[92:93] offset:3072 nt
.Lmy_ln1_next:
	s_add_u32 s8, s8, s9
	s_cmp_lt_u32 s8, s14
	s_cbranch_scc1 .Lmy_ln1_loop
.Lmy_ln1_done:
	s_branch .LBB0_210
	v_mov_b32_e32 v1, v194
	v_mov_b32_e32 v0, v194
	v_readlane_b32 s0, v253, 0
	v_ashrrev_i32_e32 v0, 6, v0
	s_movk_i32 s1, 0x2100
	v_lshl_add_u32 v49, s0, 3, v0
	v_cmp_gt_i32_e32 vcc, s1, v49
	s_and_saveexec_b64 s[8:9], vcc
	s_cbranch_execz .LBB0_210
	v_lshlrev_b32_e32 v1, 2, v1
	v_and_b32_e32 v48, 0xfc, v1
	v_and_b32_e32 v1, 64, v197
	v_add_u32_e32 v1, 64, v1
	v_xor_b32_e32 v3, 32, v197
	v_cmp_lt_i32_e32 vcc, v3, v1
	v_or_b32_e32 v2, 0x100, v48
	v_readlane_b32 s10, v254, 5
	v_cndmask_b32_e32 v3, v197, v3, vcc
	v_lshlrev_b32_e32 v122, 2, v3
	v_xor_b32_e32 v3, 16, v197
	v_cmp_lt_i32_e32 vcc, v3, v1
	v_readlane_b32 s12, v254, 7
	s_waitcnt vmcnt(1)
	v_or_b32_e32 v4, 0x200, v48
	v_cndmask_b32_e32 v3, v197, v3, vcc
	v_lshlrev_b32_e32 v123, 2, v3
	v_xor_b32_e32 v3, 8, v197
	v_cmp_lt_i32_e32 vcc, v3, v1
	v_readlane_b32 s2, v253, 9
	v_readlane_b32 s11, v254, 6
	v_cndmask_b32_e32 v3, v197, v3, vcc
	v_lshlrev_b32_e32 v124, 2, v3
	v_xor_b32_e32 v3, 4, v197
	v_cmp_lt_i32_e32 vcc, v3, v1
	v_readlane_b32 s13, v254, 8
	v_lshlrev_b32_e32 v8, 2, v2
	v_cndmask_b32_e32 v3, v197, v3, vcc
	v_mov_b32_e32 v9, v173
	v_or_b32_e32 v6, 0x300, v48
	v_lshlrev_b32_e32 v125, 2, v3
	v_xor_b32_e32 v3, 2, v197
	v_readlane_b32 s3, v253, 10
	v_lshl_add_u64 v[54:55], s[10:11], 0, v[8:9]
	v_lshl_add_u64 v[56:57], s[12:13], 0, v[8:9]
	v_lshlrev_b32_e32 v8, 2, v4
	v_cmp_lt_i32_e32 vcc, v3, v1
	s_load_dword s1, s[2:3], 0x0
	v_lshlrev_b32_e32 v172, 2, v48
	v_lshl_add_u64 v[58:59], s[10:11], 0, v[8:9]
	v_lshl_add_u64 v[60:61], s[12:13], 0, v[8:9]
	v_lshlrev_b32_e32 v8, 2, v6
	v_cndmask_b32_e32 v3, v197, v3, vcc
	v_lshl_add_u64 v[50:51], s[10:11], 0, v[172:173]
	v_lshl_add_u64 v[62:63], s[10:11], 0, v[8:9]
	v_readlane_b32 s10, v253, 5
	v_lshlrev_b32_e32 v126, 2, v3
	v_xor_b32_e32 v3, 1, v197
	v_lshl_add_u64 v[64:65], s[12:13], 0, v[8:9]
	v_lshlrev_b32_e32 v8, 1, v48
	v_readlane_b32 s11, v253, 6
	v_cmp_lt_i32_e32 vcc, v3, v1
	v_lshlrev_b32_e32 v0, 2, v0
	v_lshl_add_u64 v[66:67], s[10:11], 0, v[8:9]
	v_readlane_b32 s10, v254, 1
	v_cndmask_b32_e32 v1, v197, v3, vcc
	v_readlane_b32 s11, v254, 2
	v_lshlrev_b32_e32 v127, 2, v1
	s_waitcnt lgkmcnt(0)
	s_lshl_b32 s2, s1, 3
	v_lshl_add_u64 v[52:53], s[12:13], 0, v[172:173]
	v_lshl_add_u64 v[68:69], s[10:11], 0, v[172:173]
	v_lshl_add_u32 v70, s0, 5, v0
	s_lshl_b32 s3, s1, 5
	s_mov_b64 s[10:11], 0
	v_lshlrev_b32_e32 v72, 2, v2
	v_lshlrev_b32_e32 v74, 2, v4
	v_lshlrev_b32_e32 v76, 2, v6
	s_branch .LBB0_53

; DI int ltid() { int t = threadIdx.x; asm volatile("" : "+v"(t)); return t; }
; DI int lbid() { int t = blockIdx.x; asm volatile("" : "+s"(t)); return t; }
; DI void phase_ln(const Params& P, int l, int which, int lnext, int mshift, bool final_, bool lat_only, const bf16_t* Y, bool first) {
;     float* X = (float*)(P.ws + OFF_X);
;     const LnSpec sp{l, which, lnext, mshift, final_, nullptr, Y, first ? P.in[0] : X, first ? P.in[2] : X + (size_t)RL * 1024};
;     const int lane = ltid() & 63, wave = ltid() >> 6;
;     const int nq = ((final_ || lat_only) ? RL : RT) / 4;
;     for (int q = lbid() * NWAVE + wave; q < nq; q += gridDim.x * NWAVE) ln_rows<4>(P, sp, 4 * q, 1, lane);
.Lmy_ln2_done:
	s_branch .LBB0_70
	v_mov_b32_e32 v1, v194
	v_mov_b32_e32 v0, v194
	s_and_b64 s[0:1], s[66:67], exec
	s_movk_i32 s0, 0x2000
	v_ashrrev_i32_e32 v0, 6, v0
	s_cselect_b32 s2, s0, 0x2100
	v_readlane_b32 s0, v253, 0
	s_nop 1
	v_lshl_add_u32 v49, s0, 3, v0
	v_cmp_gt_i32_e32 vcc, s2, v49
	s_and_saveexec_b64 s[4:5], vcc
	s_cbranch_execz .LBB0_70
	v_lshlrev_b32_e32 v1, 2, v1
	v_and_b32_e32 v48, 0xfc, v1
	v_and_b32_e32 v1, 64, v197
	v_add_u32_e32 v1, 64, v1
	v_xor_b32_e32 v3, 32, v197
	s_and_b64 s[8:9], s[66:67], exec
	v_cmp_lt_i32_e32 vcc, v3, v1
	v_readlane_b32 s8, v253, 9
	v_readlane_b32 s9, v253, 10
	v_cndmask_b32_e32 v3, v197, v3, vcc
	v_lshlrev_b32_e32 v110, 2, v3
	v_xor_b32_e32 v3, 16, v197
	v_cmp_lt_i32_e32 vcc, v3, v1
	s_load_dword s11, s[8:9], 0x0
	s_movk_i32 s1, 0x4000
	v_cndmask_b32_e32 v3, v197, v3, vcc
	v_lshlrev_b32_e32 v111, 2, v3
	v_xor_b32_e32 v3, 8, v197
	v_cmp_lt_i32_e32 vcc, v3, v1
	v_readlane_b32 s12, v254, 11
	s_cselect_b32 s1, s1, 0x1000
	v_cndmask_b32_e32 v3, v197, v3, vcc
	v_lshlrev_b32_e32 v112, 2, v3
	v_xor_b32_e32 v3, 4, v197
	s_cselect_b32 s3, 5, 0
	s_waitcnt lgkmcnt(0)
	s_lshl_b32 s10, s11, 3
	v_readlane_b32 s24, v254, 23
	v_cmp_lt_i32_e32 vcc, v3, v1
	v_readlane_b32 s25, v254, 24
	s_add_u32 s8, s24, s1
	v_cndmask_b32_e32 v3, v197, v3, vcc
	s_addc_u32 s9, s25, 0
	v_lshlrev_b32_e32 v172, 2, v48
	v_lshlrev_b32_e32 v113, 2, v3
	v_xor_b32_e32 v3, 2, v197
	v_lshl_add_u64 v[50:51], s[8:9], 0, v[172:173]
	v_readlane_b32 s8, v253, 3
	v_cmp_lt_i32_e32 vcc, v3, v1
	v_lshlrev_b32_e32 v8, 1, v48
	v_mov_b32_e32 v9, v173
	v_readlane_b32 s9, v253, 4
	v_cndmask_b32_e32 v3, v197, v3, vcc
	v_lshlrev_b32_e32 v114, 2, v3
	v_lshl_add_u64 v[54:55], s[8:9], 0, v[8:9]
	v_readlane_b32 s8, v254, 1
	v_xor_b32_e32 v3, 1, v197
	v_readlane_b32 s26, v254, 25
	v_readlane_b32 s9, v254, 2
	v_cmp_lt_i32_e32 vcc, v3, v1
	v_readlane_b32 s13, v254, 12
	v_readlane_b32 s27, v254, 26
	s_add_u32 s12, s26, s1
	v_lshl_add_u64 v[56:57], s[8:9], 0, v[172:173]
	v_readlane_b32 s8, v253, 5
	v_or_b32_e32 v2, 0x100, v48
	s_waitcnt vmcnt(1)
	v_or_b32_e32 v4, 0x200, v48
	v_or_b32_e32 v6, 0x300, v48
	v_cndmask_b32_e32 v1, v197, v3, vcc
	s_addc_u32 s13, s27, 0
	v_readlane_b32 s9, v253, 6
	v_lshlrev_b32_e32 v0, 2, v0
	v_lshlrev_b32_e32 v115, 2, v1
	v_lshl_add_u64 v[52:53], s[12:13], 0, v[172:173]
	v_lshl_add_u64 v[58:59], s[8:9], 0, v[8:9]
	v_lshl_add_u32 v60, s0, 5, v0
	s_lshl_b32 s11, s11, 5
	s_mov_b64 s[8:9], 0
	v_lshlrev_b32_e32 v62, 2, v2
	v_lshlrev_b32_e32 v64, 2, v4
	v_lshlrev_b32_e32 v66, 2, v6
	v_readlane_b32 s14, v254, 13
	v_readlane_b32 s15, v254, 14
	v_readlane_b32 s16, v254, 15
	v_readlane_b32 s17, v254, 16
	v_readlane_b32 s18, v254, 17
	v_readlane_b32 s19, v254, 18
	v_readlane_b32 s20, v254, 19
	v_readlane_b32 s21, v254, 20
	v_readlane_b32 s22, v254, 21
	v_readlane_b32 s23, v254, 22
	s_branch .LBB0_36

; DI int ltid() { int t = threadIdx.x; asm volatile("" : "+v"(t)); return t; }
; DI int lbid() { int t = blockIdx.x; asm volatile("" : "+s"(t)); return t; }
; DI void phase_ln(const Params& P, int l, int which, int lnext, int mshift, bool final_, bool lat_only, const bf16_t* Y, bool first) {
;     float* X = (float*)(P.ws + OFF_X);
;     const LnSpec sp{l, which, lnext, mshift, final_, nullptr, Y, first ? P.in[0] : X, first ? P.in[2] : X + (size_t)RL * 1024};
;     const int lane = ltid() & 63, wave = ltid() >> 6;
;     const int nq = ((final_ || lat_only) ? RL : RT) / 4;
;     for (int q = lbid() * NWAVE + wave; q < nq; q += gridDim.x * NWAVE) ln_rows<4>(P, sp, 4 * q, 1, lane);
.Lmy_ln3_done:
	s_branch .LBB0_215
	v_mov_b32_e32 v1, v194
	v_mov_b32_e32 v0, v194
	v_readlane_b32 s3, v253, 0
	v_ashrrev_i32_e32 v0, 6, v0
	s_movk_i32 s0, 0x2000
	v_lshl_add_u32 v94, s3, 3, v0
	v_cmp_gt_i32_e32 vcc, s0, v94
	s_and_saveexec_b64 s[0:1], vcc
	s_movk_i32 s14, 0x1fff
	s_mov_b32 s15, 0x800000
	s_mov_b32 s16, 0x3fb504f3
	s_mov_b32 s18, 0x358637bd
	s_mov_b32 s20, 0x3a800000
	s_cbranch_execz .LBB0_215
	v_and_b32_e32 v2, 64, v197
	v_add_u32_e32 v2, 64, v2
	v_xor_b32_e32 v3, 32, v197
	v_cmp_lt_i32_e32 vcc, v3, v2
	v_lshlrev_b32_e32 v1, 2, v1
	v_and_b32_e32 v1, 0xfc, v1
	v_cndmask_b32_e32 v3, v197, v3, vcc
	v_lshlrev_b32_e32 v95, 2, v3
	v_xor_b32_e32 v3, 16, v197
	v_cmp_lt_i32_e32 vcc, v3, v2
	v_lshlrev_b32_e32 v172, 2, v1
	v_readlane_b32 s10, v254, 9
	v_cndmask_b32_e32 v3, v197, v3, vcc
	v_lshlrev_b32_e32 v96, 2, v3
	v_xor_b32_e32 v3, 8, v197
	v_cmp_lt_i32_e32 vcc, v3, v2
	v_readlane_b32 s12, v254, 27
	v_readlane_b32 s8, v253, 9
	v_cndmask_b32_e32 v3, v197, v3, vcc
	v_lshlrev_b32_e32 v97, 2, v3
	v_xor_b32_e32 v3, 4, v197
	v_cmp_lt_i32_e32 vcc, v3, v2
	v_readlane_b32 s11, v254, 10
	v_readlane_b32 s13, v254, 28
	v_cndmask_b32_e32 v3, v197, v3, vcc
	v_lshlrev_b32_e32 v98, 2, v3
	v_xor_b32_e32 v3, 2, v197
	v_cmp_lt_i32_e32 vcc, v3, v2
	v_readlane_b32 s9, v253, 10
	s_load_dword s8, s[8:9], 0x0
	v_cndmask_b32_e32 v3, v197, v3, vcc
	v_lshlrev_b32_e32 v99, 2, v3
	v_xor_b32_e32 v3, 1, v197
	v_cmp_lt_i32_e32 vcc, v3, v2
	v_lshl_add_u64 v[32:33], s[10:11], 0, v[172:173]
	v_lshlrev_b32_e32 v0, 2, v0
	v_cndmask_b32_e32 v2, v197, v3, vcc
	v_lshlrev_b32_e32 v100, 2, v2
	v_or_b32_e32 v2, 0x400, v172
	v_mov_b32_e32 v3, v173
	v_lshl_add_u64 v[36:37], s[10:11], 0, v[2:3]
	v_lshl_add_u64 v[38:39], s[12:13], 0, v[2:3]
	v_or_b32_e32 v2, 0x800, v172
	v_lshl_add_u64 v[40:41], s[10:11], 0, v[2:3]
	v_lshl_add_u64 v[42:43], s[12:13], 0, v[2:3]
	v_or_b32_e32 v2, 0xc00, v172
	v_lshl_add_u64 v[44:45], s[10:11], 0, v[2:3]
	v_readlane_b32 s10, v254, 1
	v_readlane_b32 s11, v254, 2
	v_lshl_add_u64 v[46:47], s[12:13], 0, v[2:3]
	v_lshlrev_b32_e32 v2, 1, v1
	v_lshl_add_u64 v[48:49], s[10:11], 0, v[172:173]
	v_readlane_b32 s10, v253, 5
	v_readlane_b32 s11, v253, 6
	s_waitcnt lgkmcnt(0)
	s_lshl_b32 s2, s8, 3
	v_lshl_add_u64 v[34:35], s[12:13], 0, v[172:173]
	v_lshl_add_u64 v[50:51], s[10:11], 0, v[2:3]
	v_lshl_add_u64 v[52:53], s[92:93], 0, v[172:173]
	v_lshl_add_u32 v54, s3, 5, v0
	s_lshl_b32 s3, s8, 5
	s_mov_b64 s[8:9], 0

; DI int ltid() { int t = threadIdx.x; asm volatile("" : "+v"(t)); return t; }
; DI int lbid() { int t = blockIdx.x; asm volatile("" : "+s"(t)); return t; }
; DI void phase_ln(const Params& P, int l, int which, int lnext, int mshift, bool final_, bool lat_only, const bf16_t* Y, bool first) {
;     float* X = (float*)(P.ws + OFF_X);
;     const LnSpec sp{l, which, lnext, mshift, final_, nullptr, Y, first ? P.in[0] : X, first ? P.in[2] : X + (size_t)RL * 1024};
;     const int lane = ltid() & 63, wave = ltid() >> 6;
;     const int nq = ((final_ || lat_only) ? RL : RT) / 4;
;     for (int q = lbid() * NWAVE + wave; q < nq; q += gridDim.x * NWAVE) ln_rows<4>(P, sp, 4 * q, 1, lane);
.Lmy_ln4_done:
	s_branch .LBB0_1747
	v_mov_b32_e32 v1, v194
	v_mov_b32_e32 v0, v194
	v_readlane_b32 s0, v253, 0
	v_ashrrev_i32_e32 v0, 6, v0
	s_movk_i32 s1, 0x2100
	v_lshl_add_u32 v49, s0, 3, v0
	v_cmp_gt_i32_e32 vcc, s1, v49
	s_and_saveexec_b64 s[4:5], vcc
	s_cbranch_execz .LBB0_1747
	v_lshlrev_b32_e32 v1, 2, v1
	v_and_b32_e32 v48, 0xfc, v1
	v_and_b32_e32 v1, 64, v197
	v_add_u32_e32 v1, 64, v1
	v_xor_b32_e32 v3, 32, v197
	v_cmp_lt_i32_e32 vcc, v3, v1
	s_and_b64 s[2:3], s[66:67], exec
	s_mov_b32 s1, s63
	v_cndmask_b32_e32 v3, v197, v3, vcc
	v_lshlrev_b32_e32 v108, 2, v3
	v_xor_b32_e32 v3, 16, v197
	v_readlane_b32 s60, v254, 11
	v_readlane_b32 s2, v254, 3
	v_cmp_lt_i32_e32 vcc, v3, v1
	v_readlane_b32 s64, v254, 15
	v_readlane_b32 s65, v254, 16
	v_readlane_b32 s3, v254, 4
	v_cndmask_b32_e32 v3, v197, v3, vcc
	s_cselect_b32 s9, s3, s65
	s_cselect_b32 s8, s2, s64
	v_lshlrev_b32_e32 v109, 2, v3
	v_xor_b32_e32 v3, 8, v197
	v_readlane_b32 s2, v253, 9
	v_cmp_lt_i32_e32 vcc, v3, v1
	v_readlane_b32 s3, v253, 10
	s_load_dword s14, s[2:3], 0x0
	v_cndmask_b32_e32 v3, v197, v3, vcc
	v_lshlrev_b32_e32 v110, 2, v3
	v_xor_b32_e32 v3, 4, v197
	v_cmp_lt_i32_e32 vcc, v3, v1
	v_readlane_b32 s16, v254, 1
	v_readlane_b32 s17, v254, 2
	v_cndmask_b32_e32 v3, v197, v3, vcc
	v_readlane_b32 s61, v254, 12
	v_readlane_b32 s63, v254, 14
	v_lshlrev_b32_e32 v111, 2, v3
	v_xor_b32_e32 v3, 2, v197
	v_readlane_b32 s72, v254, 23
	s_mov_b32 s63, s1
	s_cselect_b32 s7, s17, s61
	s_cselect_b32 s6, s16, s60
	s_cselect_b32 s1, 0x3000, 0
	v_cmp_lt_i32_e32 vcc, v3, v1
	s_cselect_b32 s2, 5, 0
	s_waitcnt lgkmcnt(0)
	s_lshl_b32 s3, s14, 3
	v_readlane_b32 s73, v254, 24
	v_cndmask_b32_e32 v3, v197, v3, vcc
	s_add_u32 s10, s72, s1
	v_readlane_b32 s74, v254, 25
	v_lshlrev_b32_e32 v112, 2, v3
	v_xor_b32_e32 v3, 1, v197
	s_addc_u32 s11, s73, 0
	v_lshlrev_b32_e32 v172, 2, v48
	v_readlane_b32 s66, v254, 17
	v_readlane_b32 s67, v254, 18
	v_readlane_b32 s75, v254, 26
	v_cmp_lt_i32_e32 vcc, v3, v1
	s_add_u32 s12, s74, s1
	v_lshl_add_u64 v[50:51], s[10:11], 0, v[172:173]
	v_readlane_b32 s10, v253, 5
	v_readlane_b32 s66, v254, 63
	v_or_b32_e32 v2, 0x100, v48
	s_waitcnt vmcnt(1)
	v_or_b32_e32 v4, 0x200, v48
	v_or_b32_e32 v6, 0x300, v48
	v_cndmask_b32_e32 v1, v197, v3, vcc
	s_addc_u32 s13, s75, 0
	v_lshlrev_b32_e32 v8, 1, v48
	v_mov_b32_e32 v9, v173
	v_readlane_b32 s11, v253, 6
	v_lshlrev_b32_e32 v0, 2, v0
	v_readlane_b32 s67, v252, 0
	v_lshlrev_b32_e32 v113, 2, v1
	v_lshl_add_u64 v[52:53], s[12:13], 0, v[172:173]
	v_lshl_add_u64 v[54:55], s[10:11], 0, v[8:9]
	v_lshl_add_u64 v[56:57], s[16:17], 0, v[172:173]
	v_lshl_add_u32 v58, s0, 5, v0
	s_lshl_b32 s12, s14, 5
	s_mov_b64 s[10:11], 0
	v_lshlrev_b32_e32 v60, 2, v2
	v_lshlrev_b32_e32 v62, 2, v4
	v_lshlrev_b32_e32 v64, 2, v6
	v_readlane_b32 s62, v254, 13
	v_readlane_b32 s68, v254, 19
	v_readlane_b32 s69, v254, 20
	v_readlane_b32 s70, v254, 21
	v_readlane_b32 s71, v254, 22
	s_branch .LBB0_1454
